# dpp4
# speedup vs baseline: 1.0169x; 1.0089x over previous
; DEVI void ln_row(float (&x)[16], const float* __restrict__ g, const float* __restrict__ b, int lane, float* mu_out = nullptr,
;                  float* rstd_out = nullptr) {
;   float s = 0.f;
; #pragma unroll
;   for (int i = 0; i < 16; ++i) s += x[i];
;   s = wave_sum(s);
;   float mu = s * (1.0f / 1024.0f);
;   float v = 0.f;
; #pragma unroll
;   for (int i = 0; i < 16; ++i) { float d = x[i] - mu; v += d * d; }
;   v = wave_sum(v);
;   float rstd = rsqrtf(v * (1.0f / 1024.0f) + 1e-5f);
;   if (mu_out) { *mu_out = mu; *rstd_out = rstd; }
; DEVI void ph_lnrouter(const Params& p, int layer, char* shm) {
;     ...
;     const int tok = it * 8 + w;
;     float x[16];
; #pragma unroll
;     for (int i = 0; i < 4; ++i) {
;       float4 v = *reinterpret_cast<const float4*>(h32 + (size_t)tok * 1024 + i * 256 + lane * 4);
;       x[i * 4] = v.x; x[i * 4 + 1] = v.y; x[i * 4 + 2] = v.z; x[i * 4 + 3] = v.w;
;     }
;     float mu_, rstd_;
;     ln_row(x, g, b, lane, &mu_, &rstd_);
;     if (lane == 0) ((float2*)(p.ws + OFF_HB))[tok] = make_float2(mu_, rstd_);
.LBB0_1072:
	v_ashrrev_i32_e32 v55, 31, v54
	s_waitcnt lgkmcnt(0)
	v_lshlrev_b64 v[0:1], 12, v[54:55]
	v_lshl_add_u64 v[0:1], v[44:45], 0, v[0:1]
	global_load_dwordx4 v[24:27], v[0:1], off
	global_load_dwordx4 v[20:23], v[0:1], off offset:1024
	global_load_dwordx4 v[16:19], v[0:1], off offset:2048
	global_load_dwordx4 v[82:85], v[0:1], off offset:3072
	v_cmp_lt_i32_e32 vcc, v61, v60
	s_nop 1
	v_cndmask_b32_e32 v0, v59, v61, vcc
	v_lshlrev_b32_e32 v69, 2, v0
	v_cmp_lt_i32_e32 vcc, v62, v60
	s_waitcnt vmcnt(3)
	v_add_f32_e32 v0, 0, v24
	v_add_f32_e32 v0, v25, v0
	v_add_f32_e32 v0, v26, v0
	v_add_f32_e32 v0, v27, v0
	s_waitcnt vmcnt(2)
	v_add_f32_e32 v0, v20, v0
	v_add_f32_e32 v0, v21, v0
	v_add_f32_e32 v0, v22, v0
	v_add_f32_e32 v0, v23, v0
	s_waitcnt vmcnt(1)
	v_add_f32_e32 v0, v16, v0
	v_add_f32_e32 v0, v17, v0
	v_add_f32_e32 v0, v18, v0
	v_add_f32_e32 v0, v19, v0
	s_waitcnt vmcnt(0)
	v_add_f32_e32 v0, v82, v0
	v_add_f32_e32 v0, v83, v0
	v_add_f32_e32 v0, v84, v0
	v_add_f32_e32 v0, v85, v0
	ds_bpermute_b32 v1, v69, v0
	v_cndmask_b32_e32 v2, v59, v62, vcc
	v_lshlrev_b32_e32 v71, 2, v2
	v_cmp_lt_i32_e32 vcc, v63, v60
	s_waitcnt lgkmcnt(0)
	v_add_f32_e32 v0, v0, v1
	ds_bpermute_b32 v1, v71, v0
	v_cndmask_b32_e32 v2, v59, v63, vcc
	v_lshlrev_b32_e32 v70, 2, v2
	v_cmp_lt_i32_e32 vcc, v64, v60
	s_waitcnt lgkmcnt(0)
	v_add_f32_e32 v0, v0, v1
	s_nop 1
	v_mov_b32_dpp v1, v0 row_ror:8 row_mask:0xf bank_mask:0xf
	v_cndmask_b32_e32 v2, v59, v64, vcc
	v_lshlrev_b32_e32 v72, 2, v2
	v_cmp_lt_i32_e32 vcc, v65, v60
	s_waitcnt lgkmcnt(0)
	v_add_f32_e32 v0, v0, v1
	s_nop 1
	v_mov_b32_dpp v1, v0 row_half_mirror row_mask:0xf bank_mask:0xf
	s_nop 1
	v_mov_b32_dpp v1, v1 quad_perm:[3,2,1,0] row_mask:0xf bank_mask:0xf
	v_cndmask_b32_e32 v3, v59, v65, vcc
	v_lshlrev_b32_e32 v74, 2, v3
	v_cmp_lt_i32_e32 vcc, v66, v60
	s_waitcnt lgkmcnt(0)
	v_add_f32_e32 v8, v0, v1
	s_nop 1
	v_mov_b32_dpp v9, v8 quad_perm:[2,3,0,1] row_mask:0xf bank_mask:0xf
	v_cndmask_b32_e32 v2, v59, v66, vcc
	v_lshlrev_b32_e32 v73, 2, v2
	global_load_dwordx4 v[40:43], v[46:47], off
	global_load_dwordx4 v[36:39], v[46:47], off offset:1024
	global_load_dwordx4 v[0:3], v[48:49], off
	global_load_dwordx4 v[4:7], v[48:49], off offset:1024
	s_waitcnt lgkmcnt(0)
	v_add_f32_e32 v56, v8, v9
	global_load_dwordx4 v[32:35], v[46:47], off offset:2048
	global_load_dwordx4 v[28:31], v[46:47], off offset:3072
	global_load_dwordx4 v[8:11], v[48:49], off offset:2048
	global_load_dwordx4 v[12:15], v[48:49], off offset:3072
	s_nop 1
	v_mov_b32_dpp v57, v56 quad_perm:[1,0,3,2] row_mask:0xf bank_mask:0xf
	s_waitcnt lgkmcnt(0)
	v_add_f32_e32 v57, v56, v57
	v_fmamk_f32 v79, v57, 0xba800000, v25
	v_fmamk_f32 v80, v57, 0xba800000, v24
	v_fmamk_f32 v24, v57, 0xba800000, v18
	v_mul_f32_e32 v18, v79, v79
	v_fmamk_f32 v78, v57, 0xba800000, v26
	v_fmac_f32_e32 v18, v80, v80
	v_fmac_f32_e32 v27, 0xba800000, v57
	v_fmac_f32_e32 v18, v78, v78
	v_fmamk_f32 v77, v57, 0xba800000, v20
	v_fmac_f32_e32 v18, v27, v27
	v_fmamk_f32 v76, v57, 0xba800000, v21
	v_fmac_f32_e32 v18, v77, v77
	v_fmamk_f32 v75, v57, 0xba800000, v22
	v_fmac_f32_e32 v18, v76, v76
	v_fmac_f32_e32 v23, 0xba800000, v57
	v_fmac_f32_e32 v18, v75, v75
	v_fmamk_f32 v26, v57, 0xba800000, v16
	v_fmac_f32_e32 v18, v23, v23
	v_fmamk_f32 v25, v57, 0xba800000, v17
	v_fmac_f32_e32 v18, v26, v26
	v_mul_f32_e32 v56, 0x3a800000, v57
	v_fmac_f32_e32 v18, v25, v25
	v_fmac_f32_e32 v19, 0xba800000, v57
	v_pk_add_f32 v[20:21], v[82:83], v[56:57] op_sel_hi:[1,0] neg_lo:[0,1] neg_hi:[0,1]
	v_fmac_f32_e32 v18, v24, v24
	v_pk_mul_f32 v[82:83], v[20:21], v[20:21]
	v_fmac_f32_e32 v18, v19, v19
	v_pk_add_f32 v[16:17], v[84:85], v[56:57] op_sel_hi:[1,0] neg_lo:[0,1] neg_hi:[0,1]
	v_add_f32_e32 v18, v82, v18
	v_pk_mul_f32 v[84:85], v[16:17], v[16:17]
	v_add_f32_e32 v18, v83, v18
	v_add_f32_e32 v18, v84, v18
	v_add_f32_e32 v18, v85, v18
	ds_bpermute_b32 v22, v69, v18
	s_waitcnt lgkmcnt(0)
	v_add_f32_e32 v18, v18, v22
	ds_bpermute_b32 v22, v71, v18
	s_waitcnt lgkmcnt(0)
	v_add_f32_e32 v18, v18, v22
	s_nop 1
	v_mov_b32_dpp v22, v18 row_ror:8 row_mask:0xf bank_mask:0xf
	s_waitcnt lgkmcnt(0)
	v_add_f32_e32 v18, v18, v22
	s_nop 1
	v_mov_b32_dpp v22, v18 row_half_mirror row_mask:0xf bank_mask:0xf
	s_nop 1
	v_mov_b32_dpp v22, v22 quad_perm:[3,2,1,0] row_mask:0xf bank_mask:0xf
	s_waitcnt lgkmcnt(0)
	v_add_f32_e32 v18, v18, v22
	s_nop 1
	v_mov_b32_dpp v22, v18 quad_perm:[2,3,0,1] row_mask:0xf bank_mask:0xf
	s_waitcnt lgkmcnt(0)
	v_add_f32_e32 v18, v18, v22
	s_nop 1
	v_mov_b32_dpp v22, v18 quad_perm:[1,0,3,2] row_mask:0xf bank_mask:0xf
	s_waitcnt lgkmcnt(0)
	v_add_f32_e32 v18, v18, v22
	v_fmamk_f32 v18, v18, 0x3a800000, v67
	v_mul_f32_e32 v22, 0x4b800000, v18
	v_cmp_gt_f32_e32 vcc, s19, v18
	s_nop 1
	v_cndmask_b32_e32 v18, v18, v22, vcc
	v_rsq_f32_e32 v18, v18
	s_nop 0
	v_mul_f32_e32 v22, 0x45800000, v18
	v_cndmask_b32_e32 v57, v18, v22, vcc
	s_and_saveexec_b64 s[16:17], s[2:3]
	s_cbranch_execz .LBB0_1074
	v_lshl_add_u64 v[82:83], v[54:55], 3, s[14:15]
	global_store_dwordx2 v[82:83], v[56:57], off
; DEVI void ln_row(float (&x)[16], const float* __restrict__ g, const float* __restrict__ b, int lane, float* mu_out = nullptr,
;                  float* rstd_out = nullptr) {
;     ...
; #pragma unroll
;   for (int i = 0; i < 4; ++i) {
;     float4 gg = *reinterpret_cast<const float4*>(g + i * 256 + lane * 4);
;     float4 bb = *reinterpret_cast<const float4*>(b + i * 256 + lane * 4);
;     x[i * 4 + 0] = (x[i * 4 + 0] - mu) * rstd * gg.x + bb.x;
;     x[i * 4 + 1] = (x[i * 4 + 1] - mu) * rstd * gg.y + bb.y;
;     x[i * 4 + 2] = (x[i * 4 + 2] - mu) * rstd * gg.z + bb.z;
;     x[i * 4 + 3] = (x[i * 4 + 3] - mu) * rstd * gg.w + bb.w;
;   }
; DEVI void ph_lnrouter(const Params& p, int layer, char* shm) {
;     ...
;     float le[16];
; #pragma unroll
;     for (int e = 0; e < 16; ++e) {
;       float a0 = 0.f;
; #pragma unroll
;       for (int i = 0; i < 4; ++i) {
;         float4 wv = *reinterpret_cast<const float4*>(Wt + e * 1024 + i * 256 + lane * 4);
;         a0 += x[i * 4] * wv.x + x[i * 4 + 1] * wv.y + x[i * 4 + 2] * wv.z + x[i * 4 + 3] * wv.w;
;       }
;       le[e] = a0;
;     }
.LBB0_1074:
	s_or_b64 exec, exec, s[16:17]
	v_mul_f32_e32 v18, v80, v57
	s_waitcnt vmcnt(5)
	v_fma_f32 v18, v40, v18, v0
	v_mul_f32_e32 v0, v79, v57
	v_fma_f32 v22, v41, v0, v1
	v_mul_f32_e32 v1, v27, v57
	v_mul_f32_e32 v0, v78, v57
	v_fmac_f32_e32 v3, v43, v1
	v_mul_f32_e32 v1, v77, v57
	v_fma_f32 v0, v42, v0, v2
	s_waitcnt vmcnt(4)
	v_fma_f32 v2, v36, v1, v4
	v_mul_f32_e32 v1, v76, v57
	v_fma_f32 v4, v37, v1, v5
	v_mul_f32_e32 v5, v23, v57
	v_mul_f32_e32 v1, v75, v57
	v_fmac_f32_e32 v7, v39, v5
	v_mul_f32_e32 v5, v26, v57
	v_fma_f32 v1, v38, v1, v6
	s_waitcnt vmcnt(1)
	v_fma_f32 v6, v32, v5, v8
	v_mul_f32_e32 v5, v25, v57
	v_fma_f32 v8, v33, v5, v9
	v_mul_f32_e32 v5, v24, v57
	ds_read_b128 v[24:27], v58
	v_mul_f32_e32 v9, v19, v57
	v_fma_f32 v5, v34, v5, v10
	v_fmac_f32_e32 v11, v35, v9
	v_mul_f32_e32 v9, v20, v57
	v_mul_f32_e32 v10, v21, v57
	s_waitcnt vmcnt(0)
	v_fma_f32 v9, v28, v9, v12
	v_fma_f32 v10, v29, v10, v13
	v_mul_f32_e32 v12, v16, v57
	v_mul_f32_e32 v13, v17, v57
	v_fma_f32 v12, v30, v12, v14
	v_fmac_f32_e32 v15, v13, v31
	ds_read_b128 v[28:31], v58 offset:1024
	s_waitcnt lgkmcnt(1)
	v_mul_f32_e32 v13, v22, v25
	v_fmac_f32_e32 v13, v18, v24
	v_fmac_f32_e32 v13, v0, v26
	v_fmac_f32_e32 v13, v3, v27
	ds_read_b128 v[24:27], v58 offset:2048
	s_waitcnt lgkmcnt(1)
	v_mul_f32_e32 v14, v4, v29
	v_fmac_f32_e32 v14, v2, v28
	v_fmac_f32_e32 v14, v1, v30
	v_add_f32_e32 v13, 0, v13
	v_fmac_f32_e32 v14, v7, v31
	ds_read_b128 v[28:31], v58 offset:3072
	v_add_f32_e32 v13, v13, v14
	s_waitcnt lgkmcnt(1)
	v_mul_f32_e32 v14, v8, v25
	v_fmac_f32_e32 v14, v6, v24
	v_fmac_f32_e32 v14, v5, v26
	v_fmac_f32_e32 v14, v11, v27
	ds_read_b128 v[24:27], v58 offset:4096
	v_add_f32_e32 v13, v13, v14
	s_waitcnt lgkmcnt(1)
	v_mul_f32_e32 v14, v10, v29
	v_fmac_f32_e32 v14, v9, v28
	v_fmac_f32_e32 v14, v12, v30
	v_fmac_f32_e32 v14, v15, v31
	ds_read_b128 v[28:31], v58 offset:5120
	v_add_f32_e32 v13, v13, v14
	s_waitcnt lgkmcnt(1)
	v_mul_f32_e32 v14, v22, v25
	v_fmac_f32_e32 v14, v18, v24
	v_fmac_f32_e32 v14, v0, v26
	v_fmac_f32_e32 v14, v3, v27
	ds_read_b128 v[24:27], v58 offset:6144
	s_waitcnt lgkmcnt(1)
	v_mul_f32_e32 v16, v4, v29
	v_fmac_f32_e32 v16, v2, v28
	v_fmac_f32_e32 v16, v1, v30
	v_add_f32_e32 v14, 0, v14
	v_fmac_f32_e32 v16, v7, v31
	ds_read_b128 v[28:31], v58 offset:7168
	v_add_f32_e32 v14, v14, v16
	s_waitcnt lgkmcnt(1)
	v_mul_f32_e32 v16, v8, v25
	v_fmac_f32_e32 v16, v6, v24
	v_fmac_f32_e32 v16, v5, v26
	v_fmac_f32_e32 v16, v11, v27
	ds_read_b128 v[24:27], v58 offset:8192
	v_add_f32_e32 v14, v14, v16
	s_waitcnt lgkmcnt(1)
	v_mul_f32_e32 v16, v10, v29
	v_fmac_f32_e32 v16, v9, v28
	v_fmac_f32_e32 v16, v12, v30
	v_fmac_f32_e32 v16, v15, v31
	ds_read_b128 v[28:31], v58 offset:9216
	v_add_f32_e32 v14, v14, v16
	s_waitcnt lgkmcnt(1)
	v_mul_f32_e32 v16, v22, v25
	v_fmac_f32_e32 v16, v18, v24
	v_fmac_f32_e32 v16, v0, v26
	v_fmac_f32_e32 v16, v3, v27
	ds_read_b128 v[24:27], v58 offset:10240
	s_waitcnt lgkmcnt(1)
	v_mul_f32_e32 v17, v4, v29
	v_fmac_f32_e32 v17, v2, v28
	v_fmac_f32_e32 v17, v1, v30
	v_add_f32_e32 v16, 0, v16
	v_fmac_f32_e32 v17, v7, v31
	ds_read_b128 v[28:31], v58 offset:11264
	v_add_f32_e32 v16, v16, v17
	s_waitcnt lgkmcnt(1)
	v_mul_f32_e32 v17, v8, v25
	v_fmac_f32_e32 v17, v6, v24
	v_fmac_f32_e32 v17, v5, v26
	v_fmac_f32_e32 v17, v11, v27
	ds_read_b128 v[24:27], v58 offset:12288
	v_add_f32_e32 v16, v16, v17
	s_waitcnt lgkmcnt(1)
	v_mul_f32_e32 v17, v10, v29
	v_fmac_f32_e32 v17, v9, v28
	v_fmac_f32_e32 v17, v12, v30
	v_fmac_f32_e32 v17, v15, v31
	ds_read_b128 v[28:31], v58 offset:13312
	v_add_f32_e32 v16, v16, v17
	s_waitcnt lgkmcnt(1)
	v_mul_f32_e32 v17, v22, v25
	v_fmac_f32_e32 v17, v18, v24
	v_fmac_f32_e32 v17, v0, v26
	v_fmac_f32_e32 v17, v3, v27
	ds_read_b128 v[24:27], v58 offset:14336
	s_waitcnt lgkmcnt(1)
	v_mul_f32_e32 v19, v4, v29
	v_fmac_f32_e32 v19, v2, v28
	v_fmac_f32_e32 v19, v1, v30
	v_add_f32_e32 v17, 0, v17
	v_fmac_f32_e32 v19, v7, v31
	ds_read_b128 v[28:31], v58 offset:15360
	v_add_f32_e32 v17, v17, v19
	s_waitcnt lgkmcnt(1)
	v_mul_f32_e32 v19, v8, v25
	v_fmac_f32_e32 v19, v6, v24
	v_fmac_f32_e32 v19, v5, v26
	v_fmac_f32_e32 v19, v11, v27
	ds_read_b128 v[24:27], v58 offset:16384
	v_add_f32_e32 v17, v17, v19
	s_waitcnt lgkmcnt(1)
	v_mul_f32_e32 v19, v10, v29
	v_fmac_f32_e32 v19, v9, v28
	v_fmac_f32_e32 v19, v12, v30
	v_fmac_f32_e32 v19, v15, v31
	ds_read_b128 v[28:31], v58 offset:17408
	v_add_f32_e32 v17, v17, v19
	s_waitcnt lgkmcnt(1)
	v_mul_f32_e32 v19, v22, v25
	v_fmac_f32_e32 v19, v18, v24
	v_fmac_f32_e32 v19, v0, v26
	v_fmac_f32_e32 v19, v3, v27
	ds_read_b128 v[24:27], v58 offset:18432
	s_waitcnt lgkmcnt(1)
	v_mul_f32_e32 v20, v4, v29
	v_fmac_f32_e32 v20, v2, v28
	v_fmac_f32_e32 v20, v1, v30
	v_add_f32_e32 v19, 0, v19
	v_fmac_f32_e32 v20, v7, v31
	ds_read_b128 v[28:31], v58 offset:19456
	v_add_f32_e32 v19, v19, v20
	s_waitcnt lgkmcnt(1)
	v_mul_f32_e32 v20, v8, v25
	v_fmac_f32_e32 v20, v6, v24
	v_fmac_f32_e32 v20, v5, v26
	v_fmac_f32_e32 v20, v11, v27
	ds_read_b128 v[24:27], v58 offset:20480
	v_add_f32_e32 v19, v19, v20
	s_waitcnt lgkmcnt(1)
	v_mul_f32_e32 v20, v10, v29
	v_fmac_f32_e32 v20, v9, v28
	v_fmac_f32_e32 v20, v12, v30
	v_fmac_f32_e32 v20, v15, v31
	ds_read_b128 v[28:31], v58 offset:21504
	v_add_f32_e32 v19, v19, v20
	s_waitcnt lgkmcnt(1)
	v_mul_f32_e32 v20, v22, v25
	v_fmac_f32_e32 v20, v18, v24
	v_fmac_f32_e32 v20, v0, v26
	v_fmac_f32_e32 v20, v3, v27
	ds_read_b128 v[24:27], v58 offset:22528
	s_waitcnt lgkmcnt(1)
	v_mul_f32_e32 v21, v4, v29
	v_fmac_f32_e32 v21, v2, v28
	v_fmac_f32_e32 v21, v1, v30
	v_add_f32_e32 v20, 0, v20
	v_fmac_f32_e32 v21, v7, v31
	ds_read_b128 v[28:31], v58 offset:23552
	v_add_f32_e32 v20, v20, v21
	s_waitcnt lgkmcnt(1)
; DEVI void ph_lnrouter(const Params& p, int layer, char* shm) {
;     ...
;     float le[16];
; #pragma unroll
;     for (int e = 0; e < 16; ++e) {
;       float a0 = 0.f;
; #pragma unroll
;       for (int i = 0; i < 4; ++i) {
;         float4 wv = *reinterpret_cast<const float4*>(Wt + e * 1024 + i * 256 + lane * 4);
;         a0 += x[i * 4] * wv.x + x[i * 4 + 1] * wv.y + x[i * 4 + 2] * wv.z + x[i * 4 + 3] * wv.w;
;       }
;       le[e] = a0;
;     }
	v_mul_f32_e32 v21, v8, v25
	v_fmac_f32_e32 v21, v6, v24
	v_fmac_f32_e32 v21, v5, v26
	v_fmac_f32_e32 v21, v11, v27
	ds_read_b128 v[24:27], v58 offset:24576
	v_add_f32_e32 v20, v20, v21
	s_waitcnt lgkmcnt(1)
	v_mul_f32_e32 v21, v10, v29
	v_fmac_f32_e32 v21, v9, v28
	v_fmac_f32_e32 v21, v12, v30
	v_fmac_f32_e32 v21, v15, v31
	ds_read_b128 v[28:31], v58 offset:25600
	v_add_f32_e32 v20, v20, v21
	s_waitcnt lgkmcnt(1)
	v_mul_f32_e32 v21, v22, v25
	v_fmac_f32_e32 v21, v18, v24
	v_fmac_f32_e32 v21, v0, v26
	v_fmac_f32_e32 v21, v3, v27
	ds_read_b128 v[24:27], v58 offset:26624
	s_waitcnt lgkmcnt(1)
	v_mul_f32_e32 v23, v4, v29
	v_fmac_f32_e32 v23, v2, v28
	v_fmac_f32_e32 v23, v1, v30
	v_add_f32_e32 v21, 0, v21
	v_fmac_f32_e32 v23, v7, v31
	ds_read_b128 v[28:31], v58 offset:27648
	v_add_f32_e32 v21, v21, v23
	s_waitcnt lgkmcnt(1)
	v_mul_f32_e32 v23, v8, v25
	v_fmac_f32_e32 v23, v6, v24
	v_fmac_f32_e32 v23, v5, v26
	v_fmac_f32_e32 v23, v11, v27
	v_add_f32_e32 v21, v21, v23
	s_waitcnt lgkmcnt(0)
	v_mul_f32_e32 v23, v10, v29
	ds_read_b128 v[24:27], v58 offset:28672
	v_fmac_f32_e32 v23, v9, v28
	v_fmac_f32_e32 v23, v12, v30
	v_fmac_f32_e32 v23, v15, v31
	ds_read_b128 v[28:31], v58 offset:29696
	v_add_f32_e32 v21, v21, v23
	s_waitcnt lgkmcnt(1)
	v_mul_f32_e32 v23, v22, v25
	v_fmac_f32_e32 v23, v18, v24
	v_fmac_f32_e32 v23, v0, v26
	v_fmac_f32_e32 v23, v3, v27
	s_waitcnt lgkmcnt(0)
	v_mul_f32_e32 v29, v4, v29
	ds_read_b128 v[24:27], v58 offset:30720
	v_fmac_f32_e32 v29, v2, v28
	v_fmac_f32_e32 v29, v1, v30
	v_add_f32_e32 v23, 0, v23
	v_fmac_f32_e32 v29, v7, v31
	v_add_f32_e32 v23, v23, v29
	ds_read_b128 v[28:31], v58 offset:31744
	s_waitcnt lgkmcnt(1)
	v_mul_f32_e32 v25, v8, v25
	v_fmac_f32_e32 v25, v6, v24
	v_fmac_f32_e32 v25, v5, v26
	v_fmac_f32_e32 v25, v11, v27
	v_add_f32_e32 v23, v23, v25
	s_waitcnt lgkmcnt(0)
	v_mul_f32_e32 v29, v10, v29
	ds_read_b128 v[24:27], v58 offset:32768
	v_fmac_f32_e32 v29, v9, v28
	v_fmac_f32_e32 v29, v12, v30
	v_fmac_f32_e32 v29, v15, v31
	v_add_f32_e32 v23, v23, v29
	ds_read_b128 v[28:31], v58 offset:33792
	s_waitcnt lgkmcnt(1)
	v_mul_f32_e32 v25, v22, v25
	v_fmac_f32_e32 v25, v18, v24
	v_fmac_f32_e32 v25, v0, v26
	v_fmac_f32_e32 v25, v3, v27
	v_add_f32_e32 v32, 0, v25
	s_waitcnt lgkmcnt(0)
	v_mul_f32_e32 v29, v4, v29
	ds_read_b128 v[24:27], v58 offset:34816
	v_fmac_f32_e32 v29, v2, v28
	v_fmac_f32_e32 v29, v1, v30
	v_fmac_f32_e32 v29, v7, v31
	v_add_f32_e32 v32, v32, v29
	ds_read_b128 v[28:31], v58 offset:35840
	s_waitcnt lgkmcnt(1)
	v_mul_f32_e32 v25, v8, v25
	v_fmac_f32_e32 v25, v6, v24
	v_fmac_f32_e32 v25, v5, v26
	v_fmac_f32_e32 v25, v11, v27
	v_add_f32_e32 v32, v32, v25
	s_waitcnt lgkmcnt(0)
	v_mul_f32_e32 v29, v10, v29
	ds_read_b128 v[24:27], v58 offset:36864
	v_fmac_f32_e32 v29, v9, v28
	v_fmac_f32_e32 v29, v12, v30
	v_fmac_f32_e32 v29, v15, v31
	v_add_f32_e32 v32, v32, v29
	ds_read_b128 v[28:31], v58 offset:37888
	s_waitcnt lgkmcnt(1)
	v_mul_f32_e32 v25, v22, v25
	v_fmac_f32_e32 v25, v18, v24
	v_fmac_f32_e32 v25, v0, v26
	v_fmac_f32_e32 v25, v3, v27
	v_add_f32_e32 v33, 0, v25
	s_waitcnt lgkmcnt(0)
	v_mul_f32_e32 v29, v4, v29
	ds_read_b128 v[24:27], v58 offset:38912
	v_fmac_f32_e32 v29, v2, v28
	v_fmac_f32_e32 v29, v1, v30
	v_fmac_f32_e32 v29, v7, v31
	v_add_f32_e32 v33, v33, v29
	ds_read_b128 v[28:31], v58 offset:39936
	s_waitcnt lgkmcnt(1)
	v_mul_f32_e32 v25, v8, v25
	v_fmac_f32_e32 v25, v6, v24
	v_fmac_f32_e32 v25, v5, v26
	v_fmac_f32_e32 v25, v11, v27
	v_add_f32_e32 v33, v33, v25
	s_waitcnt lgkmcnt(0)
	v_mul_f32_e32 v29, v10, v29
	ds_read_b128 v[24:27], v58 offset:40960
	v_fmac_f32_e32 v29, v9, v28
	v_fmac_f32_e32 v29, v12, v30
	v_fmac_f32_e32 v29, v15, v31
	v_add_f32_e32 v33, v33, v29
	ds_read_b128 v[28:31], v58 offset:41984
	s_waitcnt lgkmcnt(1)
	v_mul_f32_e32 v25, v22, v25
	v_fmac_f32_e32 v25, v18, v24
	v_fmac_f32_e32 v25, v0, v26
	v_fmac_f32_e32 v25, v3, v27
	v_add_f32_e32 v34, 0, v25
	s_waitcnt lgkmcnt(0)
	v_mul_f32_e32 v29, v4, v29
	ds_read_b128 v[24:27], v58 offset:43008
	v_fmac_f32_e32 v29, v2, v28
	v_fmac_f32_e32 v29, v1, v30
	v_fmac_f32_e32 v29, v7, v31
	v_add_f32_e32 v34, v34, v29
	ds_read_b128 v[28:31], v58 offset:44032
	s_waitcnt lgkmcnt(1)
	v_mul_f32_e32 v25, v8, v25
	v_fmac_f32_e32 v25, v6, v24
	v_fmac_f32_e32 v25, v5, v26
	v_fmac_f32_e32 v25, v11, v27
	v_add_f32_e32 v34, v34, v25
	s_waitcnt lgkmcnt(0)
	v_mul_f32_e32 v29, v10, v29
	ds_read_b128 v[24:27], v58 offset:45056
	v_fmac_f32_e32 v29, v9, v28
	v_fmac_f32_e32 v29, v12, v30
	v_fmac_f32_e32 v29, v15, v31
	v_add_f32_e32 v34, v34, v29
	ds_read_b128 v[28:31], v58 offset:46080
	s_waitcnt lgkmcnt(1)
	v_mul_f32_e32 v25, v22, v25
	v_fmac_f32_e32 v25, v18, v24
	v_fmac_f32_e32 v25, v0, v26
	v_fmac_f32_e32 v25, v3, v27
	v_add_f32_e32 v35, 0, v25
	s_waitcnt lgkmcnt(0)
	v_mul_f32_e32 v29, v4, v29
	ds_read_b128 v[24:27], v58 offset:47104
	v_fmac_f32_e32 v29, v2, v28
	v_fmac_f32_e32 v29, v1, v30
	v_fmac_f32_e32 v29, v7, v31
	v_add_f32_e32 v35, v35, v29
	ds_read_b128 v[28:31], v58 offset:48128
	s_waitcnt lgkmcnt(1)
	v_mul_f32_e32 v25, v8, v25
	v_fmac_f32_e32 v25, v6, v24
	v_fmac_f32_e32 v25, v5, v26
	v_fmac_f32_e32 v25, v11, v27
	v_add_f32_e32 v35, v35, v25
	s_waitcnt lgkmcnt(0)
	v_mul_f32_e32 v29, v10, v29
	ds_read_b128 v[24:27], v58 offset:49152
	v_fmac_f32_e32 v29, v9, v28
	v_fmac_f32_e32 v29, v12, v30
	v_fmac_f32_e32 v29, v15, v31
	v_add_f32_e32 v35, v35, v29
	ds_read_b128 v[28:31], v58 offset:50176
	s_waitcnt lgkmcnt(1)
	v_mul_f32_e32 v25, v22, v25
	v_fmac_f32_e32 v25, v18, v24
	v_fmac_f32_e32 v25, v0, v26
	v_fmac_f32_e32 v25, v3, v27
	v_add_f32_e32 v36, 0, v25
	s_waitcnt lgkmcnt(0)
; DEVI float reduce16(float (&v)[16], int lane) {
;   {
;     bool up = (lane & 32) != 0;
; #pragma unroll
;     for (int k = 0; k < 8; ++k) {
;       float send = up ? v[k] : v[k + 8];
;       float keep = up ? v[k + 8] : v[k];
;       v[k] = keep + __shfl_xor(send, 32);
;     }
;   }
; DEVI void ph_lnrouter(const Params& p, int layer, char* shm) {
;     ...
;     float le[16];
; #pragma unroll
;     for (int e = 0; e < 16; ++e) {
;       float a0 = 0.f;
; #pragma unroll
;       for (int i = 0; i < 4; ++i) {
;         float4 wv = *reinterpret_cast<const float4*>(Wt + e * 1024 + i * 256 + lane * 4);
;         a0 += x[i * 4] * wv.x + x[i * 4 + 1] * wv.y + x[i * 4 + 2] * wv.z + x[i * 4 + 3] * wv.w;
;       }
;       le[e] = a0;
;     }
	v_mul_f32_e32 v29, v4, v29
	ds_read_b128 v[24:27], v58 offset:51200
	v_fmac_f32_e32 v29, v2, v28
	v_fmac_f32_e32 v29, v1, v30
	v_fmac_f32_e32 v29, v7, v31
	v_add_f32_e32 v36, v36, v29
	ds_read_b128 v[28:31], v58 offset:52224
	s_waitcnt lgkmcnt(1)
	v_mul_f32_e32 v25, v8, v25
	v_fmac_f32_e32 v25, v6, v24
	v_fmac_f32_e32 v25, v5, v26
	v_fmac_f32_e32 v25, v11, v27
	v_add_f32_e32 v36, v36, v25
	s_waitcnt lgkmcnt(0)
	v_mul_f32_e32 v29, v10, v29
	ds_read_b128 v[24:27], v58 offset:53248
	v_fmac_f32_e32 v29, v9, v28
	v_fmac_f32_e32 v29, v12, v30
	v_fmac_f32_e32 v29, v15, v31
	v_add_f32_e32 v36, v36, v29
	ds_read_b128 v[28:31], v58 offset:54272
	s_waitcnt lgkmcnt(1)
	v_mul_f32_e32 v25, v22, v25
	v_fmac_f32_e32 v25, v18, v24
	v_fmac_f32_e32 v25, v0, v26
	v_fmac_f32_e32 v25, v3, v27
	v_add_f32_e32 v37, 0, v25
	s_waitcnt lgkmcnt(0)
	v_mul_f32_e32 v29, v4, v29
	ds_read_b128 v[24:27], v58 offset:55296
	v_fmac_f32_e32 v29, v2, v28
	v_fmac_f32_e32 v29, v1, v30
	v_fmac_f32_e32 v29, v7, v31
	v_add_f32_e32 v37, v37, v29
	ds_read_b128 v[28:31], v58 offset:56320
	s_waitcnt lgkmcnt(1)
	v_mul_f32_e32 v25, v8, v25
	v_fmac_f32_e32 v25, v6, v24
	v_fmac_f32_e32 v25, v5, v26
	v_fmac_f32_e32 v25, v11, v27
	v_add_f32_e32 v37, v37, v25
	s_waitcnt lgkmcnt(0)
	v_mul_f32_e32 v29, v10, v29
	ds_read_b128 v[24:27], v58 offset:57344
	v_fmac_f32_e32 v29, v9, v28
	v_fmac_f32_e32 v29, v12, v30
	v_fmac_f32_e32 v29, v15, v31
	v_add_f32_e32 v37, v37, v29
	ds_read_b128 v[28:31], v58 offset:58368
	s_waitcnt lgkmcnt(1)
	v_mul_f32_e32 v25, v22, v25
	v_fmac_f32_e32 v25, v18, v24
	v_fmac_f32_e32 v25, v0, v26
	v_fmac_f32_e32 v25, v3, v27
	v_add_f32_e32 v38, 0, v25
	s_waitcnt lgkmcnt(0)
	v_mul_f32_e32 v29, v4, v29
	ds_read_b128 v[24:27], v58 offset:59392
	v_fmac_f32_e32 v29, v2, v28
	v_fmac_f32_e32 v29, v1, v30
	v_fmac_f32_e32 v29, v7, v31
	v_add_f32_e32 v38, v38, v29
	ds_read_b128 v[28:31], v58 offset:60416
	s_waitcnt lgkmcnt(1)
	v_mul_f32_e32 v25, v8, v25
	v_fmac_f32_e32 v25, v6, v24
	v_fmac_f32_e32 v25, v5, v26
	v_fmac_f32_e32 v25, v11, v27
	v_add_f32_e32 v38, v38, v25
	s_waitcnt lgkmcnt(0)
	v_mul_f32_e32 v29, v10, v29
	ds_read_b128 v[24:27], v58 offset:61440
	v_fmac_f32_e32 v29, v9, v28
	v_fmac_f32_e32 v29, v12, v30
	v_fmac_f32_e32 v29, v15, v31
	v_add_f32_e32 v38, v38, v29
	ds_read_b128 v[28:31], v58 offset:62464
	s_waitcnt lgkmcnt(1)
	v_mul_f32_e32 v25, v22, v25
	v_fmac_f32_e32 v25, v18, v24
	v_fmac_f32_e32 v25, v0, v26
	v_fmac_f32_e32 v25, v3, v27
	v_add_f32_e32 v39, 0, v25
	s_waitcnt lgkmcnt(0)
	v_mul_f32_e32 v29, v4, v29
	ds_read_b128 v[24:27], v58 offset:63488
	v_fmac_f32_e32 v29, v2, v28
	v_fmac_f32_e32 v29, v1, v30
	v_fmac_f32_e32 v29, v7, v31
	v_add_f32_e32 v39, v39, v29
	ds_read_b128 v[28:31], v58 offset:64512
	s_waitcnt lgkmcnt(1)
	v_mul_f32_e32 v25, v8, v25
	v_fmac_f32_e32 v25, v6, v24
	v_fmac_f32_e32 v25, v5, v26
	v_fmac_f32_e32 v25, v11, v27
	v_add_f32_e32 v24, v39, v25
	s_waitcnt lgkmcnt(0)
	v_mul_f32_e32 v25, v10, v29
	v_fmac_f32_e32 v25, v9, v28
	v_fmac_f32_e32 v25, v12, v30
	v_fmac_f32_e32 v25, v15, v31
	v_add_f32_e32 v24, v24, v25
	v_cndmask_b32_e64 v25, v13, v32, s[4:5]
	v_cndmask_b32_e64 v26, v14, v33, s[4:5]
	ds_bpermute_b32 v25, v69, v25
	ds_bpermute_b32 v26, v69, v26
	v_cndmask_b32_e64 v13, v32, v13, s[4:5]
	v_cndmask_b32_e64 v14, v33, v14, s[4:5]
	v_cndmask_b32_e64 v27, v16, v34, s[4:5]
	s_waitcnt lgkmcnt(1)
	v_add_f32_e32 v13, v13, v25
	s_waitcnt lgkmcnt(0)
	v_add_f32_e32 v14, v14, v26
	v_cndmask_b32_e64 v25, v17, v35, s[4:5]
	v_cndmask_b32_e64 v26, v19, v36, s[4:5]
	ds_bpermute_b32 v27, v69, v27
	ds_bpermute_b32 v25, v69, v25
	ds_bpermute_b32 v26, v69, v26
	v_cndmask_b32_e64 v16, v34, v16, s[4:5]
	v_cndmask_b32_e64 v17, v35, v17, s[4:5]
	v_cndmask_b32_e64 v19, v36, v19, s[4:5]
	s_waitcnt lgkmcnt(2)
	v_add_f32_e32 v16, v16, v27
	v_cndmask_b32_e64 v27, v20, v37, s[4:5]
	s_waitcnt lgkmcnt(1)
	v_add_f32_e32 v17, v17, v25
	s_waitcnt lgkmcnt(0)
	v_add_f32_e32 v19, v19, v26
	v_cndmask_b32_e64 v25, v21, v38, s[4:5]
	v_cndmask_b32_e64 v26, v23, v24, s[4:5]
	ds_bpermute_b32 v27, v69, v27
	ds_bpermute_b32 v25, v69, v25
	ds_bpermute_b32 v26, v69, v26
	v_cndmask_b32_e64 v20, v37, v20, s[4:5]
	v_cndmask_b32_e64 v21, v38, v21, s[4:5]
	v_cndmask_b32_e64 v23, v24, v23, s[4:5]
	s_waitcnt lgkmcnt(2)
	v_add_f32_e32 v20, v20, v27
	s_waitcnt lgkmcnt(1)
	v_add_f32_e32 v21, v21, v25
	s_waitcnt lgkmcnt(0)
; DEVI float reduce16(float (&v)[16], int lane) {
;     ...
;   {
;     bool up = (lane & 16) != 0;
; #pragma unroll
;     for (int k = 0; k < 4; ++k) {
;       float send = up ? v[k] : v[k + 4];
;       float keep = up ? v[k + 4] : v[k];
;       v[k] = keep + __shfl_xor(send, 16);
;     }
;   }
;   {
;     bool up = (lane & 8) != 0;
; #pragma unroll
;     for (int k = 0; k < 2; ++k) {
;       float send = up ? v[k] : v[k + 2];
;       float keep = up ? v[k + 2] : v[k];
;       v[k] = keep + __shfl_xor(send, 8);
;     }
;   }
;   {
;     bool up = (lane & 4) != 0;
;     float send = up ? v[0] : v[1];
;     float keep = up ? v[1] : v[0];
;     v[0] = keep + __shfl_xor(send, 4);
;   }
;   float r = v[0];
;   r += __shfl_xor(r, 2);
;   r += __shfl_xor(r, 1);
;   return r;
; DEVI void ph_lnrouter(const Params& p, int layer, char* shm) {
;     ...
;       float v = reduce16(le, lane);
;       float mx = v;
;       mx = fmaxf(mx, __shfl_xor(mx, 32));
;       mx = fmaxf(mx, __shfl_xor(mx, 16));
;       mx = fmaxf(mx, __shfl_xor(mx, 8));
;       mx = fmaxf(mx, __shfl_xor(mx, 4));
;       float ex = expf(v - mx);
;       float sm = ex;
;       sm += __shfl_xor(sm, 32);
;       sm += __shfl_xor(sm, 16);
;       sm += __shfl_xor(sm, 8);
;       sm += __shfl_xor(sm, 4);
;       int e = ((lane >> 5) & 1) * 8 + ((lane >> 4) & 1) * 4 + ((lane >> 3) & 1) * 2 + ((lane >> 2) & 1);
;       if ((lane & 3) == 0) aff[(size_t)tok * 16 + e] = ex / sm;
	v_add_f32_e32 v23, v23, v26
	v_cndmask_b32_e64 v27, v13, v19, s[6:7]
	v_cndmask_b32_e64 v13, v19, v13, s[6:7]
	v_cndmask_b32_e64 v19, v14, v20, s[6:7]
	v_cndmask_b32_e64 v14, v20, v14, s[6:7]
	v_cndmask_b32_e64 v20, v16, v21, s[6:7]
	v_cndmask_b32_e64 v24, v17, v23, s[6:7]
	ds_bpermute_b32 v27, v71, v27
	ds_bpermute_b32 v19, v71, v19
	ds_bpermute_b32 v20, v71, v20
	ds_bpermute_b32 v24, v71, v24
	v_cndmask_b32_e64 v16, v21, v16, s[6:7]
	v_cndmask_b32_e64 v17, v23, v17, s[6:7]
	s_waitcnt lgkmcnt(3)
	v_add_f32_e32 v13, v13, v27
	s_waitcnt lgkmcnt(2)
	v_add_f32_e32 v14, v14, v19
	s_waitcnt lgkmcnt(1)
	v_add_f32_e32 v16, v16, v20
	s_waitcnt lgkmcnt(0)
	v_add_f32_e32 v17, v17, v24
	v_cndmask_b32_e64 v19, v13, v16, s[8:9]
	v_cndmask_b32_e64 v20, v14, v17, s[8:9]
	s_nop 1
	v_mov_b32_dpp v19, v19 row_ror:8 row_mask:0xf bank_mask:0xf
	s_nop 1
	v_mov_b32_dpp v20, v20 row_ror:8 row_mask:0xf bank_mask:0xf
	v_cndmask_b32_e64 v13, v16, v13, s[8:9]
	v_cndmask_b32_e64 v14, v17, v14, s[8:9]
	s_waitcnt lgkmcnt(0)
	v_add_f32_e32 v13, v13, v19
	s_waitcnt lgkmcnt(0)
	v_add_f32_e32 v14, v14, v20
	v_cndmask_b32_e64 v16, v13, v14, s[10:11]
	s_nop 1
	v_mov_b32_dpp v16, v16 row_half_mirror row_mask:0xf bank_mask:0xf
	s_nop 1
	v_mov_b32_dpp v16, v16 quad_perm:[3,2,1,0] row_mask:0xf bank_mask:0xf
	v_cndmask_b32_e64 v13, v14, v13, s[10:11]
	s_waitcnt lgkmcnt(0)
	v_add_f32_e32 v13, v13, v16
	s_nop 1
	v_mov_b32_dpp v14, v13 quad_perm:[2,3,0,1] row_mask:0xf bank_mask:0xf
	s_waitcnt lgkmcnt(0)
	v_add_f32_e32 v13, v13, v14
	s_nop 1
	v_mov_b32_dpp v14, v13 quad_perm:[1,0,3,2] row_mask:0xf bank_mask:0xf
	s_waitcnt lgkmcnt(0)
	v_add_f32_e32 v13, v13, v14
	ds_bpermute_b32 v14, v69, v13
	s_waitcnt lgkmcnt(0)
	v_max_f32_e32 v14, v14, v14
	v_max_f32_e32 v14, v13, v14
	ds_bpermute_b32 v16, v71, v14
	s_waitcnt lgkmcnt(0)
	v_max_f32_e32 v16, v16, v16
	v_max_f32_e32 v14, v14, v16
	s_nop 1
	v_mov_b32_dpp v16, v14 row_ror:8 row_mask:0xf bank_mask:0xf
	s_waitcnt lgkmcnt(0)
	v_max_f32_e32 v16, v16, v16
	v_max_f32_e32 v14, v14, v16
	s_nop 1
	v_mov_b32_dpp v16, v14 row_half_mirror row_mask:0xf bank_mask:0xf
	s_nop 1
	v_mov_b32_dpp v16, v16 quad_perm:[3,2,1,0] row_mask:0xf bank_mask:0xf
	s_waitcnt lgkmcnt(0)
	v_max_f32_e32 v16, v16, v16
	v_max_f32_e32 v14, v14, v16
	v_sub_f32_e32 v13, v13, v14
	v_mul_f32_e32 v14, 0x3fb8aa3b, v13
	v_fma_f32 v16, v13, s20, -v14
	v_rndne_f32_e32 v17, v14
	v_fmac_f32_e32 v16, 0x32a5705f, v13
	v_sub_f32_e32 v14, v14, v17
	v_add_f32_e32 v14, v14, v16
	v_exp_f32_e32 v14, v14
	v_cvt_i32_f32_e32 v19, v17
	v_cmp_ngt_f32_e32 vcc, s21, v13
	v_lshlrev_b64 v[16:17], 10, v[54:55]
	v_lshl_add_u64 v[16:17], v[50:51], 0, v[16:17]
	v_ldexp_f32 v14, v14, v19
	v_cndmask_b32_e32 v14, 0, v14, vcc
	v_cmp_nlt_f32_e32 vcc, s22, v13
	v_mov_b32_e32 v19, 0
	v_cvt_pk_fp8_f32 v19, v18, v22
	v_cndmask_b32_e32 v13, v68, v14, vcc
	ds_bpermute_b32 v14, v69, v13
	v_mov_b32_e32 v18, 0
	v_cvt_pk_fp8_f32 v18, v2, v4
	v_cvt_pk_fp8_f32 v19, v0, v3 op_sel:[0,0,1]
	s_waitcnt lgkmcnt(0)
	v_add_f32_e32 v2, v13, v14
	ds_bpermute_b32 v4, v71, v2
	v_mov_b32_e32 v14, 0
	v_cvt_pk_fp8_f32 v14, v6, v8
	v_mov_b32_e32 v6, 0
	v_cvt_pk_fp8_f32 v6, v9, v10
	s_waitcnt lgkmcnt(0)
	v_add_f32_e32 v2, v2, v4
	s_nop 1
	v_mov_b32_dpp v4, v2 row_ror:8 row_mask:0xf bank_mask:0xf
	v_cvt_pk_fp8_f32 v18, v1, v7 op_sel:[0,0,1]
	v_cvt_pk_fp8_f32 v14, v5, v11 op_sel:[0,0,1]
	v_cvt_pk_fp8_f32 v6, v12, v15 op_sel:[0,0,1]
	global_store_dword v[16:17], v19, off
	global_store_dword v[16:17], v18, off offset:256
	global_store_dword v[16:17], v14, off offset:512
	global_store_dword v[16:17], v6, off offset:768
	s_waitcnt lgkmcnt(0)
	v_add_f32_e32 v0, v2, v4
	s_nop 1
	v_mov_b32_dpp v1, v0 row_half_mirror row_mask:0xf bank_mask:0xf
	s_nop 1
	v_mov_b32_dpp v1, v1 quad_perm:[3,2,1,0] row_mask:0xf bank_mask:0xf
	s_and_saveexec_b64 s[16:17], s[12:13]
	s_cbranch_execz .LBB0_1071
	s_waitcnt lgkmcnt(0)
	v_add_f32_e32 v0, v0, v1
	v_div_scale_f32 v1, s[24:25], v0, v0, v13
	v_rcp_f32_e32 v2, v1
	v_div_scale_f32 v3, vcc, v13, v0, v13
	v_fma_f32 v4, -v1, v2, 1.0
	v_fmac_f32_e32 v2, v4, v2
	v_mul_f32_e32 v4, v3, v2
	v_fma_f32 v5, -v1, v4, v3
	v_fmac_f32_e32 v4, v5, v2
	v_fma_f32 v1, -v1, v4, v3
	v_div_fmas_f32 v1, v1, v2, v4
	v_div_fixup_f32 v2, v1, v0, v13
	v_lshlrev_b64 v[0:1], 6, v[54:55]
	v_lshl_add_u64 v[0:1], v[52:53], 0, v[0:1]
	global_store_dword v[0:1], v2, off
	s_branch .LBB0_1071

; DEVI void ln_row(float (&x)[16], const float* __restrict__ g, const float* __restrict__ b, int lane, float* mu_out = nullptr,
;                  float* rstd_out = nullptr) {
;   float s = 0.f;
; #pragma unroll
;   for (int i = 0; i < 16; ++i) s += x[i];
;   s = wave_sum(s);
;   float mu = s * (1.0f / 1024.0f);
;   float v = 0.f;
; #pragma unroll
;   for (int i = 0; i < 16; ++i) { float d = x[i] - mu; v += d * d; }
;   v = wave_sum(v);
;   float rstd = rsqrtf(v * (1.0f / 1024.0f) + 1e-5f);
;   if (mu_out) { *mu_out = mu; *rstd_out = rstd; }
; DEVI void ph_lnrouter(const Params& p, int layer, char* shm) {
;     ...
;     const int tok = it * 8 + w;
;     float x[16];
; #pragma unroll
;     for (int i = 0; i < 4; ++i) {
;       float4 v = *reinterpret_cast<const float4*>(h32 + (size_t)tok * 1024 + i * 256 + lane * 4);
;       x[i * 4] = v.x; x[i * 4 + 1] = v.y; x[i * 4 + 2] = v.z; x[i * 4 + 3] = v.w;
;     }
;     float mu_, rstd_;
;     ln_row(x, g, b, lane, &mu_, &rstd_);
;     if (lane == 0) ((float2*)(p.ws + OFF_HB))[tok] = make_float2(mu_, rstd_);
.LBB0_1908:
	v_ashrrev_i32_e32 v55, 31, v54
	s_waitcnt lgkmcnt(0)
	v_lshlrev_b64 v[0:1], 12, v[54:55]
	v_lshl_add_u64 v[0:1], v[44:45], 0, v[0:1]
	global_load_dwordx4 v[24:27], v[0:1], off
	global_load_dwordx4 v[20:23], v[0:1], off offset:1024
	global_load_dwordx4 v[16:19], v[0:1], off offset:2048
	global_load_dwordx4 v[82:85], v[0:1], off offset:3072
	v_cmp_lt_i32_e32 vcc, v61, v60
	s_nop 1
	v_cndmask_b32_e32 v0, v59, v61, vcc
	v_lshlrev_b32_e32 v69, 2, v0
	v_cmp_lt_i32_e32 vcc, v62, v60
	s_waitcnt vmcnt(3)
	v_add_f32_e32 v0, 0, v24
	v_add_f32_e32 v0, v25, v0
	v_add_f32_e32 v0, v26, v0
	v_add_f32_e32 v0, v27, v0
	s_waitcnt vmcnt(2)
	v_add_f32_e32 v0, v20, v0
	v_add_f32_e32 v0, v21, v0
	v_add_f32_e32 v0, v22, v0
	v_add_f32_e32 v0, v23, v0
	s_waitcnt vmcnt(1)
	v_add_f32_e32 v0, v16, v0
	v_add_f32_e32 v0, v17, v0
	v_add_f32_e32 v0, v18, v0
	v_add_f32_e32 v0, v19, v0
	s_waitcnt vmcnt(0)
	v_add_f32_e32 v0, v82, v0
	v_add_f32_e32 v0, v83, v0
	v_add_f32_e32 v0, v84, v0
	v_add_f32_e32 v0, v85, v0
	ds_bpermute_b32 v1, v69, v0
	v_cndmask_b32_e32 v2, v59, v62, vcc
	v_lshlrev_b32_e32 v71, 2, v2
	v_cmp_lt_i32_e32 vcc, v63, v60
	s_waitcnt lgkmcnt(0)
	v_add_f32_e32 v0, v0, v1
	ds_bpermute_b32 v1, v71, v0
	v_cndmask_b32_e32 v2, v59, v63, vcc
	v_lshlrev_b32_e32 v70, 2, v2
	v_cmp_lt_i32_e32 vcc, v64, v60
	s_waitcnt lgkmcnt(0)
	v_add_f32_e32 v0, v0, v1
	s_nop 1
	v_mov_b32_dpp v1, v0 row_ror:8 row_mask:0xf bank_mask:0xf
	v_cndmask_b32_e32 v2, v59, v64, vcc
	v_lshlrev_b32_e32 v72, 2, v2
	v_cmp_lt_i32_e32 vcc, v65, v60
	s_waitcnt lgkmcnt(0)
	v_add_f32_e32 v0, v0, v1
	s_nop 1
	v_mov_b32_dpp v1, v0 row_half_mirror row_mask:0xf bank_mask:0xf
	s_nop 1
	v_mov_b32_dpp v1, v1 quad_perm:[3,2,1,0] row_mask:0xf bank_mask:0xf
	v_cndmask_b32_e32 v3, v59, v65, vcc
	v_lshlrev_b32_e32 v74, 2, v3
	v_cmp_lt_i32_e32 vcc, v66, v60
	s_waitcnt lgkmcnt(0)
	v_add_f32_e32 v8, v0, v1
	s_nop 1
	v_mov_b32_dpp v9, v8 quad_perm:[2,3,0,1] row_mask:0xf bank_mask:0xf
	v_cndmask_b32_e32 v2, v59, v66, vcc
	v_lshlrev_b32_e32 v73, 2, v2
	global_load_dwordx4 v[40:43], v[46:47], off
	global_load_dwordx4 v[36:39], v[46:47], off offset:1024
	global_load_dwordx4 v[0:3], v[48:49], off
	global_load_dwordx4 v[4:7], v[48:49], off offset:1024
	s_waitcnt lgkmcnt(0)
	v_add_f32_e32 v56, v8, v9
	global_load_dwordx4 v[32:35], v[46:47], off offset:2048
	global_load_dwordx4 v[28:31], v[46:47], off offset:3072
	global_load_dwordx4 v[8:11], v[48:49], off offset:2048
	global_load_dwordx4 v[12:15], v[48:49], off offset:3072
	s_nop 1
	v_mov_b32_dpp v57, v56 quad_perm:[1,0,3,2] row_mask:0xf bank_mask:0xf
	s_waitcnt lgkmcnt(0)
	v_add_f32_e32 v57, v56, v57
	v_fmamk_f32 v79, v57, 0xba800000, v25
	v_fmamk_f32 v80, v57, 0xba800000, v24
	v_fmamk_f32 v24, v57, 0xba800000, v18
	v_mul_f32_e32 v18, v79, v79
	v_fmamk_f32 v78, v57, 0xba800000, v26
	v_fmac_f32_e32 v18, v80, v80
	v_fmac_f32_e32 v27, 0xba800000, v57
	v_fmac_f32_e32 v18, v78, v78
	v_fmamk_f32 v77, v57, 0xba800000, v20
	v_fmac_f32_e32 v18, v27, v27
	v_fmamk_f32 v76, v57, 0xba800000, v21
	v_fmac_f32_e32 v18, v77, v77
	v_fmamk_f32 v75, v57, 0xba800000, v22
	v_fmac_f32_e32 v18, v76, v76
	v_fmac_f32_e32 v23, 0xba800000, v57
	v_fmac_f32_e32 v18, v75, v75
	v_fmamk_f32 v26, v57, 0xba800000, v16
	v_fmac_f32_e32 v18, v23, v23
	v_fmamk_f32 v25, v57, 0xba800000, v17
	v_fmac_f32_e32 v18, v26, v26
	v_mul_f32_e32 v56, 0x3a800000, v57
	v_fmac_f32_e32 v18, v25, v25
	v_fmac_f32_e32 v19, 0xba800000, v57
	v_pk_add_f32 v[20:21], v[82:83], v[56:57] op_sel_hi:[1,0] neg_lo:[0,1] neg_hi:[0,1]
	v_fmac_f32_e32 v18, v24, v24
	v_pk_mul_f32 v[82:83], v[20:21], v[20:21]
	v_fmac_f32_e32 v18, v19, v19
	v_pk_add_f32 v[16:17], v[84:85], v[56:57] op_sel_hi:[1,0] neg_lo:[0,1] neg_hi:[0,1]
	v_add_f32_e32 v18, v82, v18
	v_pk_mul_f32 v[84:85], v[16:17], v[16:17]
	v_add_f32_e32 v18, v83, v18
	v_add_f32_e32 v18, v84, v18
	v_add_f32_e32 v18, v85, v18
	ds_bpermute_b32 v22, v69, v18
	s_waitcnt lgkmcnt(0)
	v_add_f32_e32 v18, v18, v22
	ds_bpermute_b32 v22, v71, v18
	s_waitcnt lgkmcnt(0)
	v_add_f32_e32 v18, v18, v22
	s_nop 1
	v_mov_b32_dpp v22, v18 row_ror:8 row_mask:0xf bank_mask:0xf
	s_waitcnt lgkmcnt(0)
	v_add_f32_e32 v18, v18, v22
	s_nop 1
	v_mov_b32_dpp v22, v18 row_half_mirror row_mask:0xf bank_mask:0xf
	s_nop 1
	v_mov_b32_dpp v22, v22 quad_perm:[3,2,1,0] row_mask:0xf bank_mask:0xf
	s_waitcnt lgkmcnt(0)
	v_add_f32_e32 v18, v18, v22
	s_nop 1
	v_mov_b32_dpp v22, v18 quad_perm:[2,3,0,1] row_mask:0xf bank_mask:0xf
	s_waitcnt lgkmcnt(0)
	v_add_f32_e32 v18, v18, v22
	s_nop 1
	v_mov_b32_dpp v22, v18 quad_perm:[1,0,3,2] row_mask:0xf bank_mask:0xf
	s_waitcnt lgkmcnt(0)
	v_add_f32_e32 v18, v18, v22
	v_fmamk_f32 v18, v18, 0x3a800000, v67
	v_mul_f32_e32 v22, 0x4b800000, v18
	v_cmp_gt_f32_e32 vcc, s5, v18
	s_nop 1
	v_cndmask_b32_e32 v18, v18, v22, vcc
	v_rsq_f32_e32 v18, v18
	s_nop 0
	v_mul_f32_e32 v22, 0x45800000, v18
	v_cndmask_b32_e32 v57, v18, v22, vcc
	s_and_saveexec_b64 s[2:3], s[6:7]
	s_cbranch_execz .LBB0_1910
	v_lshl_add_u64 v[82:83], v[54:55], 3, s[0:1]
	global_store_dwordx2 v[82:83], v[56:57], off
; DEVI void ln_row(float (&x)[16], const float* __restrict__ g, const float* __restrict__ b, int lane, float* mu_out = nullptr,
;                  float* rstd_out = nullptr) {
;     ...
; #pragma unroll
;   for (int i = 0; i < 4; ++i) {
;     float4 gg = *reinterpret_cast<const float4*>(g + i * 256 + lane * 4);
;     float4 bb = *reinterpret_cast<const float4*>(b + i * 256 + lane * 4);
;     x[i * 4 + 0] = (x[i * 4 + 0] - mu) * rstd * gg.x + bb.x;
;     x[i * 4 + 1] = (x[i * 4 + 1] - mu) * rstd * gg.y + bb.y;
;     x[i * 4 + 2] = (x[i * 4 + 2] - mu) * rstd * gg.z + bb.z;
;     x[i * 4 + 3] = (x[i * 4 + 3] - mu) * rstd * gg.w + bb.w;
;   }
; DEVI void ph_lnrouter(const Params& p, int layer, char* shm) {
;     ...
;     for (int e = 0; e < 16; ++e) {
;       float a0 = 0.f;
; #pragma unroll
;       for (int i = 0; i < 4; ++i) {
;         float4 wv = *reinterpret_cast<const float4*>(Wt + e * 1024 + i * 256 + lane * 4);
;         a0 += x[i * 4] * wv.x + x[i * 4 + 1] * wv.y + x[i * 4 + 2] * wv.z + x[i * 4 + 3] * wv.w;
;       }
;       le[e] = a0;
;     }
.LBB0_1910:
	s_or_b64 exec, exec, s[2:3]
	v_mul_f32_e32 v18, v80, v57
	s_waitcnt vmcnt(5)
	v_fma_f32 v18, v40, v18, v0
	v_mul_f32_e32 v0, v79, v57
	v_fma_f32 v22, v41, v0, v1
	v_mul_f32_e32 v1, v27, v57
	v_mul_f32_e32 v0, v78, v57
	v_fmac_f32_e32 v3, v43, v1
	v_mul_f32_e32 v1, v77, v57
	v_fma_f32 v0, v42, v0, v2
	s_waitcnt vmcnt(4)
	v_fma_f32 v2, v36, v1, v4
	v_mul_f32_e32 v1, v76, v57
	v_fma_f32 v4, v37, v1, v5
	v_mul_f32_e32 v5, v23, v57
	v_mul_f32_e32 v1, v75, v57
	v_fmac_f32_e32 v7, v39, v5
	v_mul_f32_e32 v5, v26, v57
	v_fma_f32 v1, v38, v1, v6
	s_waitcnt vmcnt(1)
	v_fma_f32 v6, v32, v5, v8
	v_mul_f32_e32 v5, v25, v57
	v_fma_f32 v8, v33, v5, v9
	v_mul_f32_e32 v5, v24, v57
	ds_read_b128 v[24:27], v58
	v_mul_f32_e32 v9, v19, v57
	v_fma_f32 v5, v34, v5, v10
	v_fmac_f32_e32 v11, v35, v9
	v_mul_f32_e32 v9, v20, v57
	v_mul_f32_e32 v10, v21, v57
	s_waitcnt vmcnt(0)
	v_fma_f32 v9, v28, v9, v12
	v_fma_f32 v10, v29, v10, v13
	v_mul_f32_e32 v12, v16, v57
	v_mul_f32_e32 v13, v17, v57
	v_fma_f32 v12, v30, v12, v14
	v_fmac_f32_e32 v15, v13, v31
	ds_read_b128 v[28:31], v58 offset:1024
	s_waitcnt lgkmcnt(1)
	v_mul_f32_e32 v13, v22, v25
	v_fmac_f32_e32 v13, v18, v24
	v_fmac_f32_e32 v13, v0, v26
	v_fmac_f32_e32 v13, v3, v27
	ds_read_b128 v[24:27], v58 offset:2048
	s_waitcnt lgkmcnt(1)
	v_mul_f32_e32 v14, v4, v29
	v_fmac_f32_e32 v14, v2, v28
	v_fmac_f32_e32 v14, v1, v30
	v_add_f32_e32 v13, 0, v13
	v_fmac_f32_e32 v14, v7, v31
	ds_read_b128 v[28:31], v58 offset:3072
	v_add_f32_e32 v13, v13, v14
	s_waitcnt lgkmcnt(1)
	v_mul_f32_e32 v14, v8, v25
	v_fmac_f32_e32 v14, v6, v24
	v_fmac_f32_e32 v14, v5, v26
	v_fmac_f32_e32 v14, v11, v27
	ds_read_b128 v[24:27], v58 offset:4096
	v_add_f32_e32 v13, v13, v14
	s_waitcnt lgkmcnt(1)
	v_mul_f32_e32 v14, v10, v29
	v_fmac_f32_e32 v14, v9, v28
	v_fmac_f32_e32 v14, v12, v30
	v_fmac_f32_e32 v14, v15, v31
	ds_read_b128 v[28:31], v58 offset:5120
	v_add_f32_e32 v13, v13, v14
	s_waitcnt lgkmcnt(1)
	v_mul_f32_e32 v14, v22, v25
	v_fmac_f32_e32 v14, v18, v24
	v_fmac_f32_e32 v14, v0, v26
	v_fmac_f32_e32 v14, v3, v27
	ds_read_b128 v[24:27], v58 offset:6144
	s_waitcnt lgkmcnt(1)
	v_mul_f32_e32 v16, v4, v29
	v_fmac_f32_e32 v16, v2, v28
	v_fmac_f32_e32 v16, v1, v30
	v_add_f32_e32 v14, 0, v14
	v_fmac_f32_e32 v16, v7, v31
	ds_read_b128 v[28:31], v58 offset:7168
	v_add_f32_e32 v14, v14, v16
	s_waitcnt lgkmcnt(1)
	v_mul_f32_e32 v16, v8, v25
	v_fmac_f32_e32 v16, v6, v24
	v_fmac_f32_e32 v16, v5, v26
	v_fmac_f32_e32 v16, v11, v27
	ds_read_b128 v[24:27], v58 offset:8192
	v_add_f32_e32 v14, v14, v16
	s_waitcnt lgkmcnt(1)
	v_mul_f32_e32 v16, v10, v29
	v_fmac_f32_e32 v16, v9, v28
	v_fmac_f32_e32 v16, v12, v30
	v_fmac_f32_e32 v16, v15, v31
	ds_read_b128 v[28:31], v58 offset:9216
	v_add_f32_e32 v14, v14, v16
	s_waitcnt lgkmcnt(1)
	v_mul_f32_e32 v16, v22, v25
	v_fmac_f32_e32 v16, v18, v24
	v_fmac_f32_e32 v16, v0, v26
	v_fmac_f32_e32 v16, v3, v27
	ds_read_b128 v[24:27], v58 offset:10240
	s_waitcnt lgkmcnt(1)
	v_mul_f32_e32 v17, v4, v29
	v_fmac_f32_e32 v17, v2, v28
	v_fmac_f32_e32 v17, v1, v30
	v_add_f32_e32 v16, 0, v16
	v_fmac_f32_e32 v17, v7, v31
	ds_read_b128 v[28:31], v58 offset:11264
	v_add_f32_e32 v16, v16, v17
	s_waitcnt lgkmcnt(1)
	v_mul_f32_e32 v17, v8, v25
	v_fmac_f32_e32 v17, v6, v24
	v_fmac_f32_e32 v17, v5, v26
	v_fmac_f32_e32 v17, v11, v27
	ds_read_b128 v[24:27], v58 offset:12288
	v_add_f32_e32 v16, v16, v17
	s_waitcnt lgkmcnt(1)
	v_mul_f32_e32 v17, v10, v29
	v_fmac_f32_e32 v17, v9, v28
	v_fmac_f32_e32 v17, v12, v30
	v_fmac_f32_e32 v17, v15, v31
	ds_read_b128 v[28:31], v58 offset:13312
	v_add_f32_e32 v16, v16, v17
	s_waitcnt lgkmcnt(1)
	v_mul_f32_e32 v17, v22, v25
	v_fmac_f32_e32 v17, v18, v24
	v_fmac_f32_e32 v17, v0, v26
	v_fmac_f32_e32 v17, v3, v27
	ds_read_b128 v[24:27], v58 offset:14336
	s_waitcnt lgkmcnt(1)
	v_mul_f32_e32 v19, v4, v29
	v_fmac_f32_e32 v19, v2, v28
	v_fmac_f32_e32 v19, v1, v30
	v_add_f32_e32 v17, 0, v17
	v_fmac_f32_e32 v19, v7, v31
	ds_read_b128 v[28:31], v58 offset:15360
	v_add_f32_e32 v17, v17, v19
	s_waitcnt lgkmcnt(1)
	v_mul_f32_e32 v19, v8, v25
	v_fmac_f32_e32 v19, v6, v24
	v_fmac_f32_e32 v19, v5, v26
	v_fmac_f32_e32 v19, v11, v27
	ds_read_b128 v[24:27], v58 offset:16384
	v_add_f32_e32 v17, v17, v19
	s_waitcnt lgkmcnt(1)
	v_mul_f32_e32 v19, v10, v29
	v_fmac_f32_e32 v19, v9, v28
	v_fmac_f32_e32 v19, v12, v30
	v_fmac_f32_e32 v19, v15, v31
	ds_read_b128 v[28:31], v58 offset:17408
	v_add_f32_e32 v17, v17, v19
	s_waitcnt lgkmcnt(1)
	v_mul_f32_e32 v19, v22, v25
	v_fmac_f32_e32 v19, v18, v24
	v_fmac_f32_e32 v19, v0, v26
	v_fmac_f32_e32 v19, v3, v27
	ds_read_b128 v[24:27], v58 offset:18432
	s_waitcnt lgkmcnt(1)
	v_mul_f32_e32 v20, v4, v29
	v_fmac_f32_e32 v20, v2, v28
	v_fmac_f32_e32 v20, v1, v30
	v_add_f32_e32 v19, 0, v19
	v_fmac_f32_e32 v20, v7, v31
	ds_read_b128 v[28:31], v58 offset:19456
	v_add_f32_e32 v19, v19, v20
	s_waitcnt lgkmcnt(1)
	v_mul_f32_e32 v20, v8, v25
	v_fmac_f32_e32 v20, v6, v24
	v_fmac_f32_e32 v20, v5, v26
	v_fmac_f32_e32 v20, v11, v27
	ds_read_b128 v[24:27], v58 offset:20480
	v_add_f32_e32 v19, v19, v20
	s_waitcnt lgkmcnt(1)
	v_mul_f32_e32 v20, v10, v29
	v_fmac_f32_e32 v20, v9, v28
	v_fmac_f32_e32 v20, v12, v30
	v_fmac_f32_e32 v20, v15, v31
	ds_read_b128 v[28:31], v58 offset:21504
	v_add_f32_e32 v19, v19, v20
	s_waitcnt lgkmcnt(1)
	v_mul_f32_e32 v20, v22, v25
	v_fmac_f32_e32 v20, v18, v24
	v_fmac_f32_e32 v20, v0, v26
	v_fmac_f32_e32 v20, v3, v27
	ds_read_b128 v[24:27], v58 offset:22528
	s_waitcnt lgkmcnt(1)
	v_mul_f32_e32 v21, v4, v29
	v_fmac_f32_e32 v21, v2, v28
	v_fmac_f32_e32 v21, v1, v30
	v_add_f32_e32 v20, 0, v20
	v_fmac_f32_e32 v21, v7, v31
	ds_read_b128 v[28:31], v58 offset:23552
	v_add_f32_e32 v20, v20, v21
	s_waitcnt lgkmcnt(1)
; DEVI void ph_lnrouter(const Params& p, int layer, char* shm) {
;     ...
;     for (int e = 0; e < 16; ++e) {
;       float a0 = 0.f;
; #pragma unroll
;       for (int i = 0; i < 4; ++i) {
;         float4 wv = *reinterpret_cast<const float4*>(Wt + e * 1024 + i * 256 + lane * 4);
;         a0 += x[i * 4] * wv.x + x[i * 4 + 1] * wv.y + x[i * 4 + 2] * wv.z + x[i * 4 + 3] * wv.w;
;       }
;       le[e] = a0;
;     }
	v_mul_f32_e32 v21, v8, v25
	v_fmac_f32_e32 v21, v6, v24
	v_fmac_f32_e32 v21, v5, v26
	v_fmac_f32_e32 v21, v11, v27
	ds_read_b128 v[24:27], v58 offset:24576
	v_add_f32_e32 v20, v20, v21
	s_waitcnt lgkmcnt(1)
	v_mul_f32_e32 v21, v10, v29
	v_fmac_f32_e32 v21, v9, v28
	v_fmac_f32_e32 v21, v12, v30
	v_fmac_f32_e32 v21, v15, v31
	ds_read_b128 v[28:31], v58 offset:25600
	v_add_f32_e32 v20, v20, v21
	s_waitcnt lgkmcnt(1)
	v_mul_f32_e32 v21, v22, v25
	v_fmac_f32_e32 v21, v18, v24
	v_fmac_f32_e32 v21, v0, v26
	v_fmac_f32_e32 v21, v3, v27
	ds_read_b128 v[24:27], v58 offset:26624
	s_waitcnt lgkmcnt(1)
	v_mul_f32_e32 v23, v4, v29
	v_fmac_f32_e32 v23, v2, v28
	v_fmac_f32_e32 v23, v1, v30
	v_add_f32_e32 v21, 0, v21
	v_fmac_f32_e32 v23, v7, v31
	ds_read_b128 v[28:31], v58 offset:27648
	v_add_f32_e32 v21, v21, v23
	s_waitcnt lgkmcnt(1)
	v_mul_f32_e32 v23, v8, v25
	v_fmac_f32_e32 v23, v6, v24
	v_fmac_f32_e32 v23, v5, v26
	v_fmac_f32_e32 v23, v11, v27
	v_add_f32_e32 v21, v21, v23
	s_waitcnt lgkmcnt(0)
	v_mul_f32_e32 v23, v10, v29
	ds_read_b128 v[24:27], v58 offset:28672
	v_fmac_f32_e32 v23, v9, v28
	v_fmac_f32_e32 v23, v12, v30
	v_fmac_f32_e32 v23, v15, v31
	ds_read_b128 v[28:31], v58 offset:29696
	v_add_f32_e32 v21, v21, v23
	s_waitcnt lgkmcnt(1)
	v_mul_f32_e32 v23, v22, v25
	v_fmac_f32_e32 v23, v18, v24
	v_fmac_f32_e32 v23, v0, v26
	v_fmac_f32_e32 v23, v3, v27
	s_waitcnt lgkmcnt(0)
	v_mul_f32_e32 v29, v4, v29
	ds_read_b128 v[24:27], v58 offset:30720
	v_fmac_f32_e32 v29, v2, v28
	v_fmac_f32_e32 v29, v1, v30
	v_add_f32_e32 v23, 0, v23
	v_fmac_f32_e32 v29, v7, v31
	v_add_f32_e32 v23, v23, v29
	ds_read_b128 v[28:31], v58 offset:31744
	s_waitcnt lgkmcnt(1)
	v_mul_f32_e32 v25, v8, v25
	v_fmac_f32_e32 v25, v6, v24
	v_fmac_f32_e32 v25, v5, v26
	v_fmac_f32_e32 v25, v11, v27
	v_add_f32_e32 v23, v23, v25
	s_waitcnt lgkmcnt(0)
	v_mul_f32_e32 v29, v10, v29
	ds_read_b128 v[24:27], v58 offset:32768
	v_fmac_f32_e32 v29, v9, v28
	v_fmac_f32_e32 v29, v12, v30
	v_fmac_f32_e32 v29, v15, v31
	v_add_f32_e32 v23, v23, v29
	ds_read_b128 v[28:31], v58 offset:33792
	s_waitcnt lgkmcnt(1)
	v_mul_f32_e32 v25, v22, v25
	v_fmac_f32_e32 v25, v18, v24
	v_fmac_f32_e32 v25, v0, v26
	v_fmac_f32_e32 v25, v3, v27
	v_add_f32_e32 v32, 0, v25
	s_waitcnt lgkmcnt(0)
	v_mul_f32_e32 v29, v4, v29
	ds_read_b128 v[24:27], v58 offset:34816
	v_fmac_f32_e32 v29, v2, v28
	v_fmac_f32_e32 v29, v1, v30
	v_fmac_f32_e32 v29, v7, v31
	v_add_f32_e32 v32, v32, v29
	ds_read_b128 v[28:31], v58 offset:35840
	s_waitcnt lgkmcnt(1)
	v_mul_f32_e32 v25, v8, v25
	v_fmac_f32_e32 v25, v6, v24
	v_fmac_f32_e32 v25, v5, v26
	v_fmac_f32_e32 v25, v11, v27
	v_add_f32_e32 v32, v32, v25
	s_waitcnt lgkmcnt(0)
	v_mul_f32_e32 v29, v10, v29
	ds_read_b128 v[24:27], v58 offset:36864
	v_fmac_f32_e32 v29, v9, v28
	v_fmac_f32_e32 v29, v12, v30
	v_fmac_f32_e32 v29, v15, v31
	v_add_f32_e32 v32, v32, v29
	ds_read_b128 v[28:31], v58 offset:37888
	s_waitcnt lgkmcnt(1)
	v_mul_f32_e32 v25, v22, v25
	v_fmac_f32_e32 v25, v18, v24
	v_fmac_f32_e32 v25, v0, v26
	v_fmac_f32_e32 v25, v3, v27
	v_add_f32_e32 v33, 0, v25
	s_waitcnt lgkmcnt(0)
	v_mul_f32_e32 v29, v4, v29
	ds_read_b128 v[24:27], v58 offset:38912
	v_fmac_f32_e32 v29, v2, v28
	v_fmac_f32_e32 v29, v1, v30
	v_fmac_f32_e32 v29, v7, v31
	v_add_f32_e32 v33, v33, v29
	ds_read_b128 v[28:31], v58 offset:39936
	s_waitcnt lgkmcnt(1)
	v_mul_f32_e32 v25, v8, v25
	v_fmac_f32_e32 v25, v6, v24
	v_fmac_f32_e32 v25, v5, v26
	v_fmac_f32_e32 v25, v11, v27
	v_add_f32_e32 v33, v33, v25
	s_waitcnt lgkmcnt(0)
	v_mul_f32_e32 v29, v10, v29
	ds_read_b128 v[24:27], v58 offset:40960
	v_fmac_f32_e32 v29, v9, v28
	v_fmac_f32_e32 v29, v12, v30
	v_fmac_f32_e32 v29, v15, v31
	v_add_f32_e32 v33, v33, v29
	ds_read_b128 v[28:31], v58 offset:41984
	s_waitcnt lgkmcnt(1)
	v_mul_f32_e32 v25, v22, v25
	v_fmac_f32_e32 v25, v18, v24
	v_fmac_f32_e32 v25, v0, v26
	v_fmac_f32_e32 v25, v3, v27
	v_add_f32_e32 v34, 0, v25
	s_waitcnt lgkmcnt(0)
	v_mul_f32_e32 v29, v4, v29
	ds_read_b128 v[24:27], v58 offset:43008
	v_fmac_f32_e32 v29, v2, v28
	v_fmac_f32_e32 v29, v1, v30
	v_fmac_f32_e32 v29, v7, v31
	v_add_f32_e32 v34, v34, v29
	ds_read_b128 v[28:31], v58 offset:44032
	s_waitcnt lgkmcnt(1)
	v_mul_f32_e32 v25, v8, v25
	v_fmac_f32_e32 v25, v6, v24
	v_fmac_f32_e32 v25, v5, v26
	v_fmac_f32_e32 v25, v11, v27
	v_add_f32_e32 v34, v34, v25
	s_waitcnt lgkmcnt(0)
	v_mul_f32_e32 v29, v10, v29
	ds_read_b128 v[24:27], v58 offset:45056
	v_fmac_f32_e32 v29, v9, v28
	v_fmac_f32_e32 v29, v12, v30
	v_fmac_f32_e32 v29, v15, v31
	v_add_f32_e32 v34, v34, v29
	ds_read_b128 v[28:31], v58 offset:46080
	s_waitcnt lgkmcnt(1)
	v_mul_f32_e32 v25, v22, v25
	v_fmac_f32_e32 v25, v18, v24
	v_fmac_f32_e32 v25, v0, v26
	v_fmac_f32_e32 v25, v3, v27
	v_add_f32_e32 v35, 0, v25
	s_waitcnt lgkmcnt(0)
	v_mul_f32_e32 v29, v4, v29
	ds_read_b128 v[24:27], v58 offset:47104
	v_fmac_f32_e32 v29, v2, v28
	v_fmac_f32_e32 v29, v1, v30
	v_fmac_f32_e32 v29, v7, v31
	v_add_f32_e32 v35, v35, v29
	ds_read_b128 v[28:31], v58 offset:48128
	s_waitcnt lgkmcnt(1)
	v_mul_f32_e32 v25, v8, v25
	v_fmac_f32_e32 v25, v6, v24
	v_fmac_f32_e32 v25, v5, v26
	v_fmac_f32_e32 v25, v11, v27
	v_add_f32_e32 v35, v35, v25
	s_waitcnt lgkmcnt(0)
	v_mul_f32_e32 v29, v10, v29
	ds_read_b128 v[24:27], v58 offset:49152
	v_fmac_f32_e32 v29, v9, v28
	v_fmac_f32_e32 v29, v12, v30
	v_fmac_f32_e32 v29, v15, v31
	v_add_f32_e32 v35, v35, v29
	ds_read_b128 v[28:31], v58 offset:50176
	s_waitcnt lgkmcnt(1)
	v_mul_f32_e32 v25, v22, v25
	v_fmac_f32_e32 v25, v18, v24
	v_fmac_f32_e32 v25, v0, v26
	v_fmac_f32_e32 v25, v3, v27
	v_add_f32_e32 v36, 0, v25
	s_waitcnt lgkmcnt(0)
; DEVI float reduce16(float (&v)[16], int lane) {
;   {
;     bool up = (lane & 32) != 0;
; #pragma unroll
;     for (int k = 0; k < 8; ++k) {
;       float send = up ? v[k] : v[k + 8];
;       float keep = up ? v[k + 8] : v[k];
;       v[k] = keep + __shfl_xor(send, 32);
;     }
;   }
;   {
;     bool up = (lane & 16) != 0;
; #pragma unroll
;     for (int k = 0; k < 4; ++k) {
;       float send = up ? v[k] : v[k + 4];
;       float keep = up ? v[k + 4] : v[k];
;       v[k] = keep + __shfl_xor(send, 16);
;     }
;   }
; DEVI void ph_lnrouter(const Params& p, int layer, char* shm) {
;     ...
;     for (int e = 0; e < 16; ++e) {
;       float a0 = 0.f;
; #pragma unroll
;       for (int i = 0; i < 4; ++i) {
;         float4 wv = *reinterpret_cast<const float4*>(Wt + e * 1024 + i * 256 + lane * 4);
;         a0 += x[i * 4] * wv.x + x[i * 4 + 1] * wv.y + x[i * 4 + 2] * wv.z + x[i * 4 + 3] * wv.w;
;       }
;       le[e] = a0;
;     }
	v_mul_f32_e32 v29, v4, v29
	ds_read_b128 v[24:27], v58 offset:51200
	v_fmac_f32_e32 v29, v2, v28
	v_fmac_f32_e32 v29, v1, v30
	v_fmac_f32_e32 v29, v7, v31
	v_add_f32_e32 v36, v36, v29
	ds_read_b128 v[28:31], v58 offset:52224
	s_waitcnt lgkmcnt(1)
	v_mul_f32_e32 v25, v8, v25
	v_fmac_f32_e32 v25, v6, v24
	v_fmac_f32_e32 v25, v5, v26
	v_fmac_f32_e32 v25, v11, v27
	v_add_f32_e32 v36, v36, v25
	s_waitcnt lgkmcnt(0)
	v_mul_f32_e32 v29, v10, v29
	ds_read_b128 v[24:27], v58 offset:53248
	v_fmac_f32_e32 v29, v9, v28
	v_fmac_f32_e32 v29, v12, v30
	v_fmac_f32_e32 v29, v15, v31
	v_add_f32_e32 v36, v36, v29
	ds_read_b128 v[28:31], v58 offset:54272
	s_waitcnt lgkmcnt(1)
	v_mul_f32_e32 v25, v22, v25
	v_fmac_f32_e32 v25, v18, v24
	v_fmac_f32_e32 v25, v0, v26
	v_fmac_f32_e32 v25, v3, v27
	v_add_f32_e32 v37, 0, v25
	s_waitcnt lgkmcnt(0)
	v_mul_f32_e32 v29, v4, v29
	ds_read_b128 v[24:27], v58 offset:55296
	v_fmac_f32_e32 v29, v2, v28
	v_fmac_f32_e32 v29, v1, v30
	v_fmac_f32_e32 v29, v7, v31
	v_add_f32_e32 v37, v37, v29
	ds_read_b128 v[28:31], v58 offset:56320
	s_waitcnt lgkmcnt(1)
	v_mul_f32_e32 v25, v8, v25
	v_fmac_f32_e32 v25, v6, v24
	v_fmac_f32_e32 v25, v5, v26
	v_fmac_f32_e32 v25, v11, v27
	v_add_f32_e32 v37, v37, v25
	s_waitcnt lgkmcnt(0)
	v_mul_f32_e32 v29, v10, v29
	ds_read_b128 v[24:27], v58 offset:57344
	v_fmac_f32_e32 v29, v9, v28
	v_fmac_f32_e32 v29, v12, v30
	v_fmac_f32_e32 v29, v15, v31
	v_add_f32_e32 v37, v37, v29
	ds_read_b128 v[28:31], v58 offset:58368
	s_waitcnt lgkmcnt(1)
	v_mul_f32_e32 v25, v22, v25
	v_fmac_f32_e32 v25, v18, v24
	v_fmac_f32_e32 v25, v0, v26
	v_fmac_f32_e32 v25, v3, v27
	v_add_f32_e32 v38, 0, v25
	s_waitcnt lgkmcnt(0)
	v_mul_f32_e32 v29, v4, v29
	ds_read_b128 v[24:27], v58 offset:59392
	v_fmac_f32_e32 v29, v2, v28
	v_fmac_f32_e32 v29, v1, v30
	v_fmac_f32_e32 v29, v7, v31
	v_add_f32_e32 v38, v38, v29
	ds_read_b128 v[28:31], v58 offset:60416
	s_waitcnt lgkmcnt(1)
	v_mul_f32_e32 v25, v8, v25
	v_fmac_f32_e32 v25, v6, v24
	v_fmac_f32_e32 v25, v5, v26
	v_fmac_f32_e32 v25, v11, v27
	v_add_f32_e32 v38, v38, v25
	s_waitcnt lgkmcnt(0)
	v_mul_f32_e32 v29, v10, v29
	ds_read_b128 v[24:27], v58 offset:61440
	v_fmac_f32_e32 v29, v9, v28
	v_fmac_f32_e32 v29, v12, v30
	v_fmac_f32_e32 v29, v15, v31
	v_add_f32_e32 v38, v38, v29
	ds_read_b128 v[28:31], v58 offset:62464
	s_waitcnt lgkmcnt(1)
	v_mul_f32_e32 v25, v22, v25
	v_fmac_f32_e32 v25, v18, v24
	v_fmac_f32_e32 v25, v0, v26
	v_fmac_f32_e32 v25, v3, v27
	v_add_f32_e32 v39, 0, v25
	s_waitcnt lgkmcnt(0)
	v_mul_f32_e32 v29, v4, v29
	ds_read_b128 v[24:27], v58 offset:63488
	v_fmac_f32_e32 v29, v2, v28
	v_fmac_f32_e32 v29, v1, v30
	v_fmac_f32_e32 v29, v7, v31
	v_add_f32_e32 v39, v39, v29
	ds_read_b128 v[28:31], v58 offset:64512
	s_waitcnt lgkmcnt(1)
	v_mul_f32_e32 v25, v8, v25
	v_fmac_f32_e32 v25, v6, v24
	v_fmac_f32_e32 v25, v5, v26
	v_fmac_f32_e32 v25, v11, v27
	v_add_f32_e32 v24, v39, v25
	s_waitcnt lgkmcnt(0)
	v_mul_f32_e32 v25, v10, v29
	v_fmac_f32_e32 v25, v9, v28
	v_fmac_f32_e32 v25, v12, v30
	v_fmac_f32_e32 v25, v15, v31
	v_add_f32_e32 v24, v24, v25
	v_cndmask_b32_e64 v25, v13, v32, s[8:9]
	v_cndmask_b32_e64 v26, v14, v33, s[8:9]
	ds_bpermute_b32 v25, v69, v25
	ds_bpermute_b32 v26, v69, v26
	v_cndmask_b32_e64 v13, v32, v13, s[8:9]
	v_cndmask_b32_e64 v14, v33, v14, s[8:9]
	v_cndmask_b32_e64 v27, v16, v34, s[8:9]
	s_waitcnt lgkmcnt(1)
	v_add_f32_e32 v13, v13, v25
	s_waitcnt lgkmcnt(0)
	v_add_f32_e32 v14, v14, v26
	v_cndmask_b32_e64 v25, v17, v35, s[8:9]
	v_cndmask_b32_e64 v26, v19, v36, s[8:9]
	ds_bpermute_b32 v27, v69, v27
	ds_bpermute_b32 v25, v69, v25
	ds_bpermute_b32 v26, v69, v26
	v_cndmask_b32_e64 v16, v34, v16, s[8:9]
	v_cndmask_b32_e64 v17, v35, v17, s[8:9]
	v_cndmask_b32_e64 v19, v36, v19, s[8:9]
	s_waitcnt lgkmcnt(2)
	v_add_f32_e32 v16, v16, v27
	v_cndmask_b32_e64 v27, v20, v37, s[8:9]
	s_waitcnt lgkmcnt(1)
	v_add_f32_e32 v17, v17, v25
	s_waitcnt lgkmcnt(0)
	v_add_f32_e32 v19, v19, v26
	v_cndmask_b32_e64 v25, v21, v38, s[8:9]
	v_cndmask_b32_e64 v26, v23, v24, s[8:9]
	ds_bpermute_b32 v27, v69, v27
	ds_bpermute_b32 v25, v69, v25
	ds_bpermute_b32 v26, v69, v26
	v_cndmask_b32_e64 v20, v37, v20, s[8:9]
	v_cndmask_b32_e64 v21, v38, v21, s[8:9]
	v_cndmask_b32_e64 v23, v24, v23, s[8:9]
	s_waitcnt lgkmcnt(2)
	v_add_f32_e32 v20, v20, v27
	s_waitcnt lgkmcnt(1)
	v_add_f32_e32 v21, v21, v25
	s_waitcnt lgkmcnt(0)
	v_add_f32_e32 v23, v23, v26
	v_cndmask_b32_e64 v27, v13, v19, s[10:11]
	v_cndmask_b32_e64 v13, v19, v13, s[10:11]
	v_cndmask_b32_e64 v19, v14, v20, s[10:11]
	v_cndmask_b32_e64 v14, v20, v14, s[10:11]
	v_cndmask_b32_e64 v20, v16, v21, s[10:11]
	v_cndmask_b32_e64 v24, v17, v23, s[10:11]
	ds_bpermute_b32 v27, v71, v27
	ds_bpermute_b32 v19, v71, v19
	ds_bpermute_b32 v20, v71, v20
	ds_bpermute_b32 v24, v71, v24
	v_cndmask_b32_e64 v16, v21, v16, s[10:11]
	v_cndmask_b32_e64 v17, v23, v17, s[10:11]
	s_waitcnt lgkmcnt(3)
	v_add_f32_e32 v13, v13, v27
	s_waitcnt lgkmcnt(2)
	v_add_f32_e32 v14, v14, v19
	s_waitcnt lgkmcnt(1)
	v_add_f32_e32 v16, v16, v20
	s_waitcnt lgkmcnt(0)
	v_add_f32_e32 v17, v17, v24
	v_cndmask_b32_e64 v19, v13, v16, s[12:13]
	v_cndmask_b32_e64 v20, v14, v17, s[12:13]
	s_nop 1
	v_mov_b32_dpp v19, v19 row_ror:8 row_mask:0xf bank_mask:0xf
	s_nop 1
	v_mov_b32_dpp v20, v20 row_ror:8 row_mask:0xf bank_mask:0xf
	v_cndmask_b32_e64 v13, v16, v13, s[12:13]
	v_cndmask_b32_e64 v14, v17, v14, s[12:13]
	s_waitcnt lgkmcnt(0)
	v_add_f32_e32 v13, v13, v19
	s_waitcnt lgkmcnt(0)
	v_add_f32_e32 v14, v14, v20
	v_cndmask_b32_e64 v16, v13, v14, s[14:15]
	s_nop 1
	v_mov_b32_dpp v16, v16 row_half_mirror row_mask:0xf bank_mask:0xf
	s_nop 1
	v_mov_b32_dpp v16, v16 quad_perm:[3,2,1,0] row_mask:0xf bank_mask:0xf
	v_cndmask_b32_e64 v13, v14, v13, s[14:15]
	s_waitcnt lgkmcnt(0)
	v_add_f32_e32 v13, v13, v16
	s_nop 1
	v_mov_b32_dpp v14, v13 quad_perm:[2,3,0,1] row_mask:0xf bank_mask:0xf
	s_waitcnt lgkmcnt(0)
	v_add_f32_e32 v13, v13, v14
	s_nop 1
	v_mov_b32_dpp v14, v13 quad_perm:[1,0,3,2] row_mask:0xf bank_mask:0xf
	s_waitcnt lgkmcnt(0)
	v_add_f32_e32 v13, v13, v14
	ds_bpermute_b32 v14, v69, v13
	s_waitcnt lgkmcnt(0)
	v_max_f32_e32 v14, v14, v14
	v_max_f32_e32 v14, v13, v14
	ds_bpermute_b32 v16, v71, v14
	s_waitcnt lgkmcnt(0)
	v_max_f32_e32 v16, v16, v16
	v_max_f32_e32 v14, v14, v16
	s_nop 1
	v_mov_b32_dpp v16, v14 row_ror:8 row_mask:0xf bank_mask:0xf
	s_waitcnt lgkmcnt(0)
	v_max_f32_e32 v16, v16, v16
	v_max_f32_e32 v14, v14, v16
	s_nop 1
	v_mov_b32_dpp v16, v14 row_half_mirror row_mask:0xf bank_mask:0xf
	s_nop 1
	v_mov_b32_dpp v16, v16 quad_perm:[3,2,1,0] row_mask:0xf bank_mask:0xf
	s_waitcnt lgkmcnt(0)
	v_max_f32_e32 v16, v16, v16
	v_max_f32_e32 v14, v14, v16
	v_sub_f32_e32 v13, v13, v14
	v_mul_f32_e32 v14, 0x3fb8aa3b, v13
	v_fma_f32 v16, v13, s18, -v14
	v_rndne_f32_e32 v17, v14
	v_fmac_f32_e32 v16, 0x32a5705f, v13
	v_sub_f32_e32 v14, v14, v17
	v_add_f32_e32 v14, v14, v16
	v_exp_f32_e32 v14, v14
	v_cvt_i32_f32_e32 v19, v17
	v_cmp_ngt_f32_e32 vcc, s19, v13
	v_lshlrev_b64 v[16:17], 10, v[54:55]
	v_lshl_add_u64 v[16:17], v[50:51], 0, v[16:17]
	v_ldexp_f32 v14, v14, v19
	v_cndmask_b32_e32 v14, 0, v14, vcc
	v_cmp_nlt_f32_e32 vcc, s20, v13
	v_mov_b32_e32 v19, 0
	v_cvt_pk_fp8_f32 v19, v18, v22
	v_cndmask_b32_e32 v13, v68, v14, vcc
	ds_bpermute_b32 v14, v69, v13
	v_mov_b32_e32 v18, 0
	v_cvt_pk_fp8_f32 v18, v2, v4
	v_cvt_pk_fp8_f32 v19, v0, v3 op_sel:[0,0,1]
	s_waitcnt lgkmcnt(0)
	v_add_f32_e32 v2, v13, v14
	ds_bpermute_b32 v4, v71, v2
	v_mov_b32_e32 v14, 0
	v_cvt_pk_fp8_f32 v14, v6, v8
	v_mov_b32_e32 v6, 0
	v_cvt_pk_fp8_f32 v6, v9, v10
	s_waitcnt lgkmcnt(0)
	v_add_f32_e32 v2, v2, v4
	s_nop 1
	v_mov_b32_dpp v4, v2 row_ror:8 row_mask:0xf bank_mask:0xf
	v_cvt_pk_fp8_f32 v18, v1, v7 op_sel:[0,0,1]
	v_cvt_pk_fp8_f32 v14, v5, v11 op_sel:[0,0,1]
	v_cvt_pk_fp8_f32 v6, v12, v15 op_sel:[0,0,1]
	global_store_dword v[16:17], v19, off
	global_store_dword v[16:17], v18, off offset:256
	global_store_dword v[16:17], v14, off offset:512
	global_store_dword v[16:17], v6, off offset:768
	s_waitcnt lgkmcnt(0)
	v_add_f32_e32 v0, v2, v4
	s_nop 1
	v_mov_b32_dpp v1, v0 row_half_mirror row_mask:0xf bank_mask:0xf
	s_nop 1
	v_mov_b32_dpp v1, v1 quad_perm:[3,2,1,0] row_mask:0xf bank_mask:0xf
	s_and_saveexec_b64 s[2:3], s[16:17]
	s_cbranch_execz .LBB0_1907
	s_waitcnt lgkmcnt(0)
	v_add_f32_e32 v0, v0, v1
	v_div_scale_f32 v1, s[22:23], v0, v0, v13
	v_rcp_f32_e32 v2, v1
	v_div_scale_f32 v3, vcc, v13, v0, v13
	v_fma_f32 v4, -v1, v2, 1.0
	v_fmac_f32_e32 v2, v4, v2
	v_mul_f32_e32 v4, v3, v2
	v_fma_f32 v5, -v1, v4, v3
	v_fmac_f32_e32 v4, v5, v2
	v_fma_f32 v1, -v1, v4, v3
	v_div_fmas_f32 v1, v1, v2, v4
	v_div_fixup_f32 v2, v1, v0, v13
	v_lshlrev_b64 v[0:1], 6, v[54:55]
	v_lshl_add_u64 v[0:1], v[52:53], 0, v[0:1]
	global_store_dword v[0:1], v2, off
	s_branch .LBB0_1907
